# v_e2_prio + static s_setprio 1 for the younger wave half (waves 4-7) in both indexer MFMA phases
# speedup vs baseline: 1.0139x; 1.0049x over previous
; #define LAS __attribute__((address_space(3)))
; __device__ __forceinline__ void idx_stream(unsigned char* ws, LAS unsigned char* lds, int bb, int bid, int G, int wave, int lane, int tid) {
;     const bf16_t* IQ = (const bf16_t*)(ws + WS_IQ) + (size_t)bb * SEQ * 2048;
;     const bf16_t* IK = (const bf16_t*)(ws + WS_IK) + (size_t)bb * SEQ * 128;
;     const float* IW = (const float*)(ws + WS_IW) + (size_t)bb * SEQ * 16;
;     _Float16* SC = (_Float16*)(ws + WS_SC);
;     constexpr int NT = 8320, PITCH = 272, TK = 128;
;     const int g0 = (int)(((long)bid * NT) / G), g1 = (int)(((long)(bid + 1) * NT) / G);
;     if (g0 >= g1) return;
;     int u = 0, pu = 0;
;     while (pu + ((u + 4) >> 2) <= g0) { pu += (u + 4) >> 2; ++u; }
.LBB0_1135:
	s_cmp_lt_i32 s42, 4
	s_cselect_b64 s[4:5], -1, 0
	s_and_b64 s[0:1], s[4:5], s[6:7]
	s_andn2_b64 vcc, exec, s[0:1]
	s_mul_hi_i32 s49, s2, 0x2080
	s_mul_i32 s48, s2, 0x2080
	s_cbranch_vccnz .LBB0_1153
	v_readlane_b32 s91, v255, 3
	s_cmp_gt_u32 s91, 3
	s_cbranch_scc0 .Lidxprio_a
	s_setprio 1
.Lidxprio_a:
	v_readlane_b32 s0, v255, 0
	v_readlane_b32 s1, v255, 1
	s_ashr_i32 s45, s44, 31
	s_or_b64 s[0:1], s[48:49], s[44:45]
	s_mov_b32 s0, 0
	s_cmp_lg_u64 s[0:1], 0
	v_mbcnt_lo_u32_b32 v0, -1, 0
	v_mbcnt_hi_u32_b32 v0, -1, v0
	s_cbranch_scc0 .LBB0_1165
	s_ashr_i32 s6, s45, 31
	s_add_u32 s0, s44, s6
	s_mov_b32 s7, s6
	s_addc_u32 s1, s45, s6
	s_xor_b64 s[10:11], s[0:1], s[6:7]
	v_cvt_f32_u32_e32 v1, s10
	v_cvt_f32_u32_e32 v2, s11
	s_sub_u32 s3, 0, s10
	s_subb_u32 s12, 0, s11
	v_fmamk_f32 v1, v2, 0x4f800000, v1
	v_rcp_f32_e32 v1, v1
	s_nop 0
	v_mul_f32_e32 v1, 0x5f7ffffc, v1
	v_mul_f32_e32 v2, 0x2f800000, v1
	v_trunc_f32_e32 v2, v2
	v_fmamk_f32 v1, v2, 0xcf800000, v1
	v_cvt_u32_f32_e32 v2, v2
	v_cvt_u32_f32_e32 v1, v1
	v_readfirstlane_b32 s13, v2
	v_readfirstlane_b32 s0, v1
	s_mul_i32 s1, s3, s13
	s_mul_hi_u32 s15, s3, s0
	s_mul_i32 s14, s12, s0
	s_add_i32 s1, s15, s1
	s_add_i32 s1, s1, s14
	s_mul_i32 s16, s3, s0
	s_mul_i32 s15, s0, s1
	s_mul_hi_u32 s17, s0, s16
	s_mul_hi_u32 s14, s0, s1
	s_add_u32 s15, s17, s15
	s_addc_u32 s14, 0, s14
	s_mul_hi_u32 s18, s13, s16
	s_mul_i32 s16, s13, s16
	s_add_u32 s15, s15, s16
	s_mul_hi_u32 s17, s13, s1
	s_addc_u32 s14, s14, s18
	s_addc_u32 s15, s17, 0
	s_mul_i32 s1, s13, s1
	s_add_u32 s1, s14, s1
	s_addc_u32 s14, 0, s15
	s_add_u32 s15, s0, s1
	s_cselect_b64 s[0:1], -1, 0
	s_cmp_lg_u64 s[0:1], 0
	s_addc_u32 s13, s13, s14
	s_mul_i32 s0, s3, s13
	s_mul_hi_u32 s1, s3, s15
	s_add_i32 s0, s1, s0
	s_mul_i32 s12, s12, s15
	s_add_i32 s0, s0, s12
	s_mul_i32 s3, s3, s15
	s_mul_hi_u32 s12, s13, s3
	s_mul_i32 s14, s13, s3
	s_mul_i32 s17, s15, s0
	s_mul_hi_u32 s3, s15, s3
	s_mul_hi_u32 s16, s15, s0
	s_add_u32 s3, s3, s17
	s_addc_u32 s16, 0, s16
	s_add_u32 s3, s3, s14
	s_mul_hi_u32 s1, s13, s0
	s_addc_u32 s3, s16, s12
	s_addc_u32 s1, s1, 0
	s_mul_i32 s0, s13, s0
	s_add_u32 s0, s3, s0
	s_addc_u32 s3, 0, s1
	s_add_u32 s14, s15, s0
	s_cselect_b64 s[0:1], -1, 0
	s_cmp_lg_u64 s[0:1], 0
	s_addc_u32 s3, s13, s3
	s_ashr_i32 s0, s49, 31
	s_add_u32 s12, s48, s0
	s_mov_b32 s1, s0
	s_addc_u32 s13, s49, s0
	s_xor_b64 s[12:13], s[12:13], s[0:1]
	s_mul_i32 s16, s12, s3
	s_mul_hi_u32 s17, s12, s14
	s_mul_hi_u32 s15, s12, s3
	s_add_u32 s16, s17, s16
	s_addc_u32 s15, 0, s15
	s_mul_hi_u32 s18, s13, s14
	s_mul_i32 s14, s13, s14
	s_add_u32 s14, s16, s14
	s_mul_hi_u32 s17, s13, s3
	s_addc_u32 s14, s15, s18
	s_addc_u32 s15, s17, 0
	s_mul_i32 s3, s13, s3
	s_add_u32 s3, s14, s3
	s_addc_u32 s18, 0, s15
	s_mul_i32 s14, s10, s18
	s_mul_hi_u32 s15, s10, s3
	s_add_i32 s14, s15, s14
	s_mul_i32 s15, s11, s3
	s_add_i32 s19, s14, s15
	s_sub_i32 s16, s13, s19
	s_mul_i32 s14, s10, s3
	s_sub_u32 s12, s12, s14
	s_cselect_b64 s[14:15], -1, 0
	s_cmp_lg_u64 s[14:15], 0
	s_subb_u32 s20, s16, s11
	s_sub_u32 s21, s12, s10
	s_cselect_b64 s[16:17], -1, 0
	s_cmp_lg_u64 s[16:17], 0
	s_subb_u32 s16, s20, 0
	s_cmp_ge_u32 s16, s11
	s_cselect_b32 s17, -1, 0
	s_cmp_ge_u32 s21, s10
	s_cselect_b32 s20, -1, 0
	s_cmp_eq_u32 s16, s11
	s_cselect_b32 s16, s20, s17
	s_add_u32 s17, s3, 1
	s_addc_u32 s20, s18, 0
	s_add_u32 s21, s3, 2
	s_addc_u32 s22, s18, 0
	s_cmp_lg_u32 s16, 0
	s_cselect_b32 s16, s21, s17
	s_cselect_b32 s17, s22, s20
	s_cmp_lg_u64 s[14:15], 0
	s_subb_u32 s13, s13, s19
	s_cmp_ge_u32 s13, s11
	s_cselect_b32 s14, -1, 0
	s_cmp_ge_u32 s12, s10
	s_cselect_b32 s10, -1, 0
	s_cmp_eq_u32 s13, s11
	s_cselect_b32 s10, s10, s14
	s_cmp_lg_u32 s10, 0
	s_cselect_b32 s11, s17, s18
	s_cselect_b32 s10, s16, s3
	s_xor_b64 s[0:1], s[0:1], s[6:7]
	s_xor_b64 s[6:7], s[10:11], s[0:1]
	s_sub_u32 s6, s6, s0
	v_cvt_f32_u32_e32 v1, s44
	s_cbranch_execnz .LBB0_1139

; #define LAS __attribute__((address_space(3)))
; __device__ __forceinline__ unsigned xb_add(unsigned* p, unsigned v) { return __hip_atomic_fetch_add(p, v, RLX_AGENT); }
; __device__ __forceinline__ unsigned xb_xcc_id() { return (unsigned)__builtin_amdgcn_s_getreg((3 << 11) | 20) & 0xFu; }
; __device__ __forceinline__ void grid_bar(unsigned* bar, volatile LAS unsigned* st, unsigned G, int wave) {
;     asm volatile("s_waitcnt vmcnt(0) lgkmcnt(0)" ::: "memory");
;     __syncthreads();
;     int l; asm volatile("v_mbcnt_lo_u32_b32 %0, -1, 0\n\tv_mbcnt_hi_u32_b32 %0, -1, %0" : "=v"(l));
;     if (wave == 0 && l == 0) {
;         const unsigned x = xb_xcc_id();
;         __builtin_amdgcn_s_waitcnt(0);
;         unsigned nloc = st[0], nx = st[1];
;         if (nloc == 0u) { xcd_barrier_complete(bar, x, G, nloc, nx); st[0] = nloc; st[1] = nx; }
;         const unsigned old = xb_add(&bar[XB_XSUB(x)], 1u);
;         const unsigned gen = old / nloc;
.LBB0_1153:
	s_setprio 0
	s_cmp_gt_i32 s43, 4
	s_cselect_b64 s[6:7], -1, 0
	s_and_b64 s[0:1], s[4:5], s[6:7]
	s_andn2_b64 vcc, exec, s[0:1]
	s_cbranch_vccnz .LBB0_1209
	s_waitcnt vmcnt(0) lgkmcnt(0)
	s_waitcnt lgkmcnt(0)
	s_barrier
	v_mbcnt_lo_u32_b32 v0, -1, 0
	v_mbcnt_hi_u32_b32 v0, -1, v0
	s_nop 0
	v_cmp_eq_u32_e32 vcc, 0, v0
	s_and_b64 s[0:1], s[36:37], vcc
	s_and_saveexec_b64 s[4:5], s[0:1]
	s_cbranch_execz .LBB0_1208
	s_add_i32 s1, 0, 0x20000
	v_mov_b32_e32 v0, s1
	s_getreg_b32 s0, hwreg(HW_REG_XCC_ID, 0, 4)
	s_waitcnt vmcnt(0) expcnt(0) lgkmcnt(0)
	ds_read_b32 v2, v0
	s_add_i32 s1, 0, 0x20004
	v_mov_b32_e32 v0, s1
	ds_read_b32 v0, v0
	s_and_b32 s0, s0, 15
	s_waitcnt lgkmcnt(1)
	v_cmp_ne_u32_e32 vcc, 0, v2
	s_cbranch_vccnz .LBB0_1172
	s_add_u32 s8, s40, 0x1000
	s_addc_u32 s9, s41, 0
	s_add_u32 s10, s40, 0x1100
	s_addc_u32 s11, s41, 0
	s_add_u32 s12, s40, 0x1200
	s_addc_u32 s13, s41, 0
	s_add_u32 s14, s40, 0x1300
	s_addc_u32 s15, s41, 0
	s_mov_b32 s1, 1
	v_mov_b32_e32 v16, 0
	s_branch .LBB0_1158

.LBB0_2955:
	s_cmp_lt_i32 s42, 7
	s_cselect_b64 s[4:5], -1, 0
	s_cmp_gt_i32 s43, 6
	s_cselect_b64 s[0:1], -1, 0
	s_and_b64 s[0:1], s[4:5], s[0:1]
	s_andn2_b64 vcc, exec, s[0:1]
	s_waitcnt lgkmcnt(0)
	s_barrier
	s_cbranch_vccnz .LBB0_2973
	v_readlane_b32 s91, v255, 3
	s_cmp_gt_u32 s91, 3
	s_cbranch_scc0 .Lidxprio_b
	s_setprio 1

; #define LAS __attribute__((address_space(3)))
; __device__ __forceinline__ unsigned xb_add(unsigned* p, unsigned v) { return __hip_atomic_fetch_add(p, v, RLX_AGENT); }
; __device__ __forceinline__ unsigned xb_xcc_id() { return (unsigned)__builtin_amdgcn_s_getreg((3 << 11) | 20) & 0xFu; }
; __device__ __forceinline__ void grid_bar(unsigned* bar, volatile LAS unsigned* st, unsigned G, int wave) {
;     asm volatile("s_waitcnt vmcnt(0) lgkmcnt(0)" ::: "memory");
;     __syncthreads();
;     int l; asm volatile("v_mbcnt_lo_u32_b32 %0, -1, 0\n\tv_mbcnt_hi_u32_b32 %0, -1, %0" : "=v"(l));
;     if (wave == 0 && l == 0) {
;         const unsigned x = xb_xcc_id();
;         __builtin_amdgcn_s_waitcnt(0);
;         unsigned nloc = st[0], nx = st[1];
;         if (nloc == 0u) { xcd_barrier_complete(bar, x, G, nloc, nx); st[0] = nloc; st[1] = nx; }
;         const unsigned old = xb_add(&bar[XB_XSUB(x)], 1u);
;         const unsigned gen = old / nloc;
.LBB0_2973:
	s_setprio 0
	s_cmp_gt_i32 s43, 7
	s_cselect_b64 s[6:7], -1, 0
	s_and_b64 s[0:1], s[4:5], s[6:7]
	s_andn2_b64 vcc, exec, s[0:1]
	s_cbranch_vccnz .LBB0_3029
	s_waitcnt vmcnt(0) lgkmcnt(0)
	s_barrier
	v_mbcnt_lo_u32_b32 v0, -1, 0
	v_mbcnt_hi_u32_b32 v0, -1, v0
	s_nop 0
	v_cmp_eq_u32_e32 vcc, 0, v0
	s_and_b64 s[0:1], s[36:37], vcc
	s_and_saveexec_b64 s[4:5], s[0:1]
	s_cbranch_execz .LBB0_3028
	s_add_i32 s1, 0, 0x20000
	v_mov_b32_e32 v0, s1
	s_getreg_b32 s0, hwreg(HW_REG_XCC_ID, 0, 4)
	s_waitcnt vmcnt(0) expcnt(0) lgkmcnt(0)
	ds_read_b32 v2, v0
	s_add_i32 s1, 0, 0x20004
	v_mov_b32_e32 v0, s1
	ds_read_b32 v0, v0
	s_and_b32 s0, s0, 15
	s_waitcnt lgkmcnt(1)
	v_cmp_ne_u32_e32 vcc, 0, v2
	s_cbranch_vccnz .LBB0_2992
	s_add_u32 s8, s40, 0x1000
	s_addc_u32 s9, s41, 0
	s_add_u32 s10, s40, 0x1100
	s_addc_u32 s11, s41, 0
	s_add_u32 s12, s40, 0x1200
	s_addc_u32 s13, s41, 0
	s_add_u32 s14, s40, 0x1300
	s_addc_u32 s15, s41, 0
	s_mov_b32 s1, 1
	v_mov_b32_e32 v16, 0
	s_branch .LBB0_2978
